# up-proj epilogue: -log2e of the sigmoid exp2 folded into the gate-branch conv taps/bias (and -ln2 into the value branch) when the per-tile tap table is staged in LDS; removes the 64 per-thread v_mul i
# speedup vs baseline: 1.0027x; 1.0027x over previous
; #define PG8_LAS __attribute__((address_space(3)))
;     __device__ __forceinline__ void operator()(f32x4 (&acc)[2][2][4][2], const Unit& u, int wr, int wc, int fr_, int fq_) const {
;     ...
;         const f32x2w wld = *(const f32x2w*)((wk < 3 ? cw + wk * NUP_ : cb) + wgv * DFF_ + u.pn * HALF + wch);
;         const int t0 = (wr * 16 + fr) * 8;
;         { const f32x4 r0 = *(const PG8_LAS f32x4*)(RS + t0), r1 = *(const PG8_LAS f32x4*)(RS + t0 + 4);
; #pragma unroll
;           for (int m = 0; m < 4; ++m)
; #pragma unroll
;             for (int bj = 0; bj < 2; ++bj)
; #pragma unroll
;                 for (int n = 0; n < 2; ++n) { acc[0][bj][m][n] *= r0[m]; acc[1][bj][m][n] *= r1[m]; } }
;         const int colb = wc * 32 + 8 * fq;
;         if (wr == 0 && fr == 15) {
; #pragma unroll
;             for (int bj = 0; bj < 2; ++bj)
; #pragma unroll
;                 for (int n = 0; n < 2; ++n) { *(PG8_LAS f32x4*)(X + bj * HALF + n * 4 + colb) = acc[1][bj][2][n]; *(PG8_LAS f32x4*)(X + 256 + bj * HALF + n * 4 + colb) = acc[1][bj][3][n]; } }
;         { float* hb = hbuf + (size_t)u.pm * 4 * NUP_ + u.pn * BM + colb;
;           if (wr == 0 && fr == 0) {
; #pragma unroll
;               for (int bj = 0; bj < 2; ++bj)
; #pragma unroll
;                   for (int n = 0; n < 2; ++n) { *(f32x4*)(hb + bj * HALF + n * 4) = acc[0][bj][0][n]; *(f32x4*)(hb + (size_t)NUP_ + bj * HALF + n * 4) = acc[0][bj][1][n]; } }
;           if (wr == 1 && fr == 15) {
; #pragma unroll
;               for (int bj = 0; bj < 2; ++bj)
; #pragma unroll
;                   for (int n = 0; n < 2; ++n) { *(f32x4*)(hb + (size_t)2 * NUP_ + bj * HALF + n * 4) = acc[1][bj][2][n]; *(f32x4*)(hb + (size_t)3 * NUP_ + bj * HALF + n * 4) = acc[1][bj][3][n]; } } }
;         *(PG8_LAS f32x2w*)(CW + t2) = wld;
.LBB0_696:
	s_or_b64 exec, exec, s[2:3]
	s_mul_i32 s3, s84, 0x2c000
	s_mul_hi_i32 s2, s84, 0x2c000
	s_add_u32 s4, s46, s3
	s_addc_u32 s5, s47, s2
	s_lshl_b32 s2, s85, 8
	s_ashr_i32 s3, s2, 31
	s_lshl_b64 s[2:3], s[2:3], 2
	s_add_u32 s2, s4, s2
	v_pk_mul_f32 v[136:137], v[92:93], v[164:165] op_sel:[0,1]
	s_addc_u32 s3, s5, s3
	v_ashrrev_i32_e32 v215, 31, v214
	v_or_b32_e32 v92, s34, v169
	v_pk_mul_f32 v[70:71], v[130:131], v[164:165] op_sel_hi:[1,0]
	v_pk_mul_f32 v[72:73], v[132:133], v[164:165] op_sel_hi:[1,0]
	v_pk_mul_f32 v[130:131], v[118:119], v[164:165] op_sel_hi:[1,0]
	v_pk_mul_f32 v[132:133], v[120:121], v[164:165] op_sel_hi:[1,0]
	v_pk_mul_f32 v[66:67], v[102:103], v[164:165] op_sel_hi:[1,0]
	v_pk_mul_f32 v[68:69], v[104:105], v[164:165] op_sel_hi:[1,0]
	v_pk_mul_f32 v[142:143], v[74:75], v[164:165] op_sel_hi:[1,0]
	v_pk_mul_f32 v[144:145], v[76:77], v[164:165] op_sel_hi:[1,0]
	v_pk_mul_f32 v[74:75], v[110:111], v[164:165] op_sel:[0,1]
	v_pk_mul_f32 v[76:77], v[112:113], v[164:165] op_sel:[0,1]
	v_pk_mul_f32 v[138:139], v[98:99], v[164:165] op_sel:[0,1]
	v_pk_mul_f32 v[140:141], v[100:101], v[164:165] op_sel:[0,1]
	v_pk_mul_f32 v[78:79], v[78:79], v[164:165] op_sel:[0,1]
	v_pk_mul_f32 v[80:81], v[80:81], v[164:165] op_sel:[0,1]
	v_pk_mul_f32 v[134:135], v[90:91], v[164:165] op_sel:[0,1]
	v_lshlrev_b32_e32 v216, 1, v170
	v_lshl_add_u32 v216, v216, 2, s72
	v_and_b32_e32 v94, 64, v170
	v_mov_b32_e32 v95, 0xbf317218
	v_cmp_eq_u32_e64 s[40:41], 0, v94
	v_mov_b32_e32 v94, 0xbfb8aa3b
	s_waitcnt vmcnt(0)
	v_cndmask_b32_e64 v94, v95, v94, s[40:41]
	v_mul_f32_e32 v162, v94, v162
	v_mul_f32_e32 v163, v94, v163
	ds_write_b64 v216, v[162:163]
	v_lshl_add_u64 v[90:91], v[214:215], 2, s[2:3]
	v_cmp_eq_u32_e64 s[4:5], 0, v92
	s_and_saveexec_b64 s[2:3], s[4:5]
	s_cbranch_execz .LBB0_698
	v_add_co_u32_e32 v92, vcc, 0xb000, v90
	global_store_dwordx4 v[90:91], v[70:73], off
	s_nop 0
	v_addc_co_u32_e32 v93, vcc, 0, v91, vcc
	global_store_dwordx4 v[92:93], v[74:77], off
	global_store_dwordx4 v[90:91], v[130:133], off offset:16
	global_store_dwordx4 v[92:93], v[138:141], off offset:16
	global_store_dwordx4 v[90:91], v[66:69], off offset:512
	global_store_dwordx4 v[92:93], v[78:81], off offset:512
	global_store_dwordx4 v[90:91], v[142:145], off offset:528
	global_store_dwordx4 v[92:93], v[134:137], off offset:528

; #define PG8_LAS __attribute__((address_space(3)))
; __device__ __forceinline__ unsigned cvt_pk_bf16(float lo, float hi) { f32x2c v = {lo, hi}; bf16x2c b = __builtin_convertvector(v, bf16x2c); return __builtin_bit_cast(unsigned, b); }
; __device__ __forceinline__ float dpp_shr1(float v, float old) { return __builtin_bit_cast(float, __builtin_amdgcn_update_dpp(__builtin_bit_cast(int, old), __builtin_bit_cast(int, v), 0x111, 0xf, 0xf, false)); }
;     __device__ __forceinline__ void operator()(f32x4 (&acc)[2][2][4][2], const Unit& u, int wr, int wc, int fr_, int fq_) const {
;     ...
;             if (wr == 1 && fr == 0) { h6g = *(const PG8_LAS f32x4*)(X + n * 4 + colb); h7g = *(const PG8_LAS f32x4*)(X + 256 + n * 4 + colb); h6v = *(const PG8_LAS f32x4*)(X + HALF + n * 4 + colb); h7v = *(const PG8_LAS f32x4*)(X + 256 + HALF + n * 4 + colb); }
; #pragma unroll
;             for (int i = 0; i < 4; ++i) { h6g[i] = dpp_shr1(acc[1][0][2][n][i], h6g[i]); h7g[i] = dpp_shr1(acc[1][0][3][n][i], h7g[i]); h6v[i] = dpp_shr1(acc[1][1][2][n][i], h6v[i]); h7v[i] = dpp_shr1(acc[1][1][3][n][i], h7v[i]); }
;             f32x4 g2 = h6g, g1 = h7g, v2 = h6v, v1 = h7v;
; #pragma unroll
;             for (int j = 0; j < 8; ++j) { const f32x4 Gc = acc[j >> 2][0][j & 3][n], Vc = acc[j >> 2][1][j & 3][n];
;                 const f32x4 gc = wg0 * g2 + wg1 * g1 + wg2 * Gc + bg, vc = wv0 * v2 + wv1 * v1 + wv2 * Vc + bv; f32x4 o;
; #pragma unroll
;                 for (int i = 0; i < 4; ++i) o[i] = gc[i] * __builtin_amdgcn_rcpf(1.0f + __builtin_amdgcn_exp2f(gc[i] * -1.4426950408889634f)) * vc[i];
;                 pk[n][j].x = cvt_pk_bf16(o[0], o[1]); pk[n][j].y = cvt_pk_bf16(o[2], o[3]);
;                 g2 = g1; g1 = Gc; v2 = v1; v1 = Vc; } }
.LBB0_704:
	s_or_b64 exec, exec, s[2:3]
	s_and_b32 s2, s84, 31
	s_cmp_eq_u32 s2, 0
	s_cselect_b64 s[2:3], -1, 0
	s_xor_b64 s[4:5], s[4:5], -1
	v_lshl_add_u32 v248, s84, 8, v248
	v_mov_b64_e32 v[232:233], s[92:93]
	s_or_b64 s[2:3], s[2:3], s[4:5]
	v_mad_i64_i32 v[232:233], s[4:5], v248, s71, v[232:233]
	v_lshl_add_u64 v[232:233], s[30:31], 1, v[232:233]
	s_waitcnt lgkmcnt(3)
	v_mov_b32_dpp v198, v150 row_shr:1 row_mask:0xf bank_mask:0xf
	s_waitcnt lgkmcnt(2)
	v_mov_b32_dpp v206, v158 row_shr:1 row_mask:0xf bank_mask:0xf
	s_waitcnt lgkmcnt(1)
	v_mov_b32_dpp v202, v146 row_shr:1 row_mask:0xf bank_mask:0xf
	s_waitcnt lgkmcnt(0)
	v_mov_b32_dpp v210, v154 row_shr:1 row_mask:0xf bank_mask:0xf
	v_mov_b32_dpp v199, v151 row_shr:1 row_mask:0xf bank_mask:0xf
	v_mov_b32_dpp v207, v159 row_shr:1 row_mask:0xf bank_mask:0xf
	v_mov_b32_dpp v203, v147 row_shr:1 row_mask:0xf bank_mask:0xf
	v_mov_b32_dpp v211, v155 row_shr:1 row_mask:0xf bank_mask:0xf
	v_mov_b32_dpp v200, v152 row_shr:1 row_mask:0xf bank_mask:0xf
	v_mov_b32_dpp v208, v160 row_shr:1 row_mask:0xf bank_mask:0xf
	v_mov_b32_dpp v204, v148 row_shr:1 row_mask:0xf bank_mask:0xf
	v_mov_b32_dpp v212, v156 row_shr:1 row_mask:0xf bank_mask:0xf
	v_mov_b32_dpp v201, v153 row_shr:1 row_mask:0xf bank_mask:0xf
	v_mov_b32_dpp v209, v161 row_shr:1 row_mask:0xf bank_mask:0xf
	v_mov_b32_dpp v205, v149 row_shr:1 row_mask:0xf bank_mask:0xf
	v_mov_b32_dpp v213, v157 row_shr:1 row_mask:0xf bank_mask:0xf
	v_lshl_add_u64 v[248:249], v[214:215], 1, v[232:233]
	s_and_saveexec_b64 s[4:5], s[2:3]
	s_xor_b64 s[4:5], exec, s[4:5]
	s_cbranch_execz .LBB0_706
	v_pk_mul_f32 v[214:215], v[110:111], v[220:221]
	v_pk_mul_f32 v[220:221], v[106:107], v[220:221]
	v_pk_fma_f32 v[214:215], v[106:107], v[228:229], v[214:215]
	v_pk_fma_f32 v[220:221], v[70:71], v[110:111], v[220:221]
	v_pk_fma_f32 v[214:215], v[70:71], v[114:115], v[214:215]
	v_pk_fma_f32 v[220:221], v[74:75], v[114:115], v[220:221]
	v_pk_add_f32 v[214:215], v[118:119], v[214:215]
	v_pk_add_f32 v[220:221], v[118:119], v[220:221]
	s_nop 0
	s_nop 0
	v_exp_f32_e32 v228, v214
	v_exp_f32_e32 v229, v215
	v_add_f32_e32 v228, 1.0, v228
	v_add_f32_e32 v229, 1.0, v229
	v_rcp_f32_e32 v228, v228
	v_rcp_f32_e32 v229, v229
	s_nop 0
	v_pk_mul_f32 v[214:215], v[214:215], v[228:229]
	v_pk_mul_f32 v[228:229], v[102:103], v[216:217]
	v_pk_mul_f32 v[216:217], v[90:91], v[216:217]
	v_pk_fma_f32 v[224:225], v[90:91], v[224:225], v[228:229]
	v_pk_fma_f32 v[216:217], v[66:67], v[102:103], v[216:217]
	v_pk_fma_f32 v[224:225], v[66:67], v[94:95], v[224:225]
	v_pk_fma_f32 v[216:217], v[78:79], v[94:95], v[216:217]
	v_pk_add_f32 v[224:225], v[98:99], v[224:225]
	v_pk_add_f32 v[216:217], v[98:99], v[216:217]
	v_pk_mul_f32 v[214:215], v[224:225], v[214:215]
	s_nop 0
	v_cvt_pk_bf16_f32 v214, v214, v215
	s_nop 0
	v_exp_f32_e32 v215, v220
	s_nop 0
	v_add_f32_e32 v215, 1.0, v215
	v_rcp_f32_e32 v224, v215
	s_nop 0
	v_exp_f32_e32 v215, v221
	s_nop 0
	v_add_f32_e32 v215, 1.0, v215
	v_rcp_f32_e32 v225, v215
	s_nop 0
	v_pk_mul_f32 v[220:221], v[220:221], v[224:225]
	s_nop 0
	v_pk_mul_f32 v[216:217], v[216:217], v[220:221]
	v_pk_mul_f32 v[220:221], v[112:113], v[222:223]
	s_nop 0
	v_pk_fma_f32 v[220:221], v[108:109], v[230:231], v[220:221]
	s_nop 0
	v_pk_fma_f32 v[220:221], v[72:73], v[116:117], v[220:221]
	s_nop 0
	v_pk_add_f32 v[220:221], v[120:121], v[220:221]
	s_nop 0
	s_nop 0
	v_exp_f32_e32 v215, v220
	s_nop 0
	v_add_f32_e32 v215, 1.0, v215
	v_rcp_f32_e32 v224, v215
	s_nop 0
	v_exp_f32_e32 v215, v221
	s_nop 0
	v_add_f32_e32 v215, 1.0, v215
	v_rcp_f32_e32 v225, v215
	s_nop 0
	v_pk_mul_f32 v[220:221], v[220:221], v[224:225]
	v_pk_mul_f32 v[224:225], v[104:105], v[218:219]
	v_pk_mul_f32 v[218:219], v[92:93], v[218:219]
	v_pk_fma_f32 v[224:225], v[92:93], v[226:227], v[224:225]
	v_pk_fma_f32 v[218:219], v[68:69], v[104:105], v[218:219]
	v_pk_fma_f32 v[224:225], v[68:69], v[96:97], v[224:225]
	v_pk_fma_f32 v[218:219], v[80:81], v[96:97], v[218:219]
	v_pk_add_f32 v[224:225], v[100:101], v[224:225]
	v_pk_add_f32 v[218:219], v[100:101], v[218:219]
	v_pk_mul_f32 v[220:221], v[224:225], v[220:221]
	v_pk_mul_f32 v[224:225], v[130:131], v[176:177]
	v_cvt_pk_bf16_f32 v215, v220, v221
	v_pk_mul_f32 v[220:221], v[108:109], v[222:223]
	v_pk_fma_f32 v[224:225], v[188:189], v[206:207], v[224:225]
	v_pk_fma_f32 v[220:221], v[72:73], v[112:113], v[220:221]
	v_pk_fma_f32 v[224:225], v[138:139], v[180:181], v[224:225]
	v_pk_fma_f32 v[220:221], v[76:77], v[116:117], v[220:221]
	v_pk_add_f32 v[224:225], v[184:185], v[224:225]
	v_pk_add_f32 v[220:221], v[120:121], v[220:221]
	s_nop 0
	s_nop 0
	s_nop 0
	v_exp_f32_e32 v222, v220
	v_exp_f32_e32 v223, v221
	s_nop 0
	v_pk_mul_f32 v[206:207], v[176:177], v[206:207]
	v_add_f32_e32 v222, 1.0, v222
	v_add_f32_e32 v223, 1.0, v223
	v_rcp_f32_e32 v222, v222
	v_rcp_f32_e32 v223, v223
	v_exp_f32_e32 v226, v224
	v_exp_f32_e32 v227, v225
	v_pk_fma_f32 v[198:199], v[188:189], v[198:199], v[206:207]
	v_pk_mul_f32 v[220:221], v[220:221], v[222:223]
	v_pk_fma_f32 v[198:199], v[130:131], v[180:181], v[198:199]
	v_add_f32_e32 v226, 1.0, v226
	v_pk_add_f32 v[198:199], v[184:185], v[198:199]
	v_add_f32_e32 v227, 1.0, v227
	s_nop 0
	s_nop 0
	v_exp_f32_e32 v206, v198
	v_exp_f32_e32 v207, v199
	v_pk_mul_f32 v[220:221], v[218:219], v[220:221]
	v_rcp_f32_e32 v226, v226
	v_rcp_f32_e32 v227, v227
	v_cvt_pk_bf16_f32 v219, v220, v221
	v_pk_mul_f32 v[220:221], v[142:143], v[162:163]
	v_pk_mul_f32 v[222:223], v[132:133], v[178:179]
	v_pk_fma_f32 v[220:221], v[194:195], v[210:211], v[220:221]
	v_pk_fma_f32 v[222:223], v[190:191], v[208:209], v[222:223]
	v_pk_fma_f32 v[220:221], v[134:135], v[168:169], v[220:221]
; __device__ __forceinline__ unsigned cvt_pk_bf16(float lo, float hi) { f32x2c v = {lo, hi}; bf16x2c b = __builtin_convertvector(v, bf16x2c); return __builtin_bit_cast(unsigned, b); }
; __device__ __forceinline__ float dpp_shr1(float v, float old) { return __builtin_bit_cast(float, __builtin_amdgcn_update_dpp(__builtin_bit_cast(int, old), __builtin_bit_cast(int, v), 0x111, 0xf, 0xf, false)); }
;     __device__ __forceinline__ void operator()(f32x4 (&acc)[2][2][4][2], const Unit& u, int wr, int wc, int fr_, int fq_) const {
;     ...
; #pragma unroll
;             for (int i = 0; i < 4; ++i) { h6g[i] = dpp_shr1(acc[1][0][2][n][i], h6g[i]); h7g[i] = dpp_shr1(acc[1][0][3][n][i], h7g[i]); h6v[i] = dpp_shr1(acc[1][1][2][n][i], h6v[i]); h7v[i] = dpp_shr1(acc[1][1][3][n][i], h7v[i]); }
;             f32x4 g2 = h6g, g1 = h7g, v2 = h6v, v1 = h7v;
; #pragma unroll
;             for (int j = 0; j < 8; ++j) { const f32x4 Gc = acc[j >> 2][0][j & 3][n], Vc = acc[j >> 2][1][j & 3][n];
;                 const f32x4 gc = wg0 * g2 + wg1 * g1 + wg2 * Gc + bg, vc = wv0 * v2 + wv1 * v1 + wv2 * Vc + bv; f32x4 o;
; #pragma unroll
;                 for (int i = 0; i < 4; ++i) o[i] = gc[i] * __builtin_amdgcn_rcpf(1.0f + __builtin_amdgcn_exp2f(gc[i] * -1.4426950408889634f)) * vc[i];
;                 pk[n][j].x = cvt_pk_bf16(o[0], o[1]); pk[n][j].y = cvt_pk_bf16(o[2], o[3]);
;                 g2 = g1; g1 = Gc; v2 = v1; v1 = Vc; } }
;         bf16_t* ap = act + (size_t)(u.pm * BM + t0) * DFF_ + u.pn * HALF + colb;
; #pragma unroll
;         for (int j = 0; j < 8; ++j) if (!(defer01 && j < 2)) *(u32x4*)(ap + (size_t)j * DFF_) = (u32x4){pk[0][j].x, pk[0][j].y, pk[1][j].x, pk[1][j].y};
	v_add_f32_e32 v206, 1.0, v206
	v_add_f32_e32 v207, 1.0, v207
	v_pk_add_f32 v[220:221], v[172:173], v[220:221]
	v_pk_mul_f32 v[224:225], v[224:225], v[226:227]
	v_pk_fma_f32 v[222:223], v[140:141], v[182:183], v[222:223]
	v_rcp_f32_e32 v206, v206
	v_rcp_f32_e32 v207, v207
	v_pk_mul_f32 v[220:221], v[220:221], v[224:225]
	v_pk_add_f32 v[222:223], v[186:187], v[222:223]
	v_pk_mul_f32 v[210:211], v[162:163], v[210:211]
	v_cvt_pk_bf16_f32 v220, v220, v221
	s_nop 0
	v_pk_fma_f32 v[202:203], v[194:195], v[202:203], v[210:211]
	v_exp_f32_e32 v221, v222
	v_pk_fma_f32 v[202:203], v[142:143], v[168:169], v[202:203]
	v_pk_mul_f32 v[198:199], v[198:199], v[206:207]
	v_pk_add_f32 v[202:203], v[172:173], v[202:203]
	v_add_f32_e32 v221, 1.0, v221
	v_pk_mul_f32 v[198:199], v[202:203], v[198:199]
	v_pk_mul_f32 v[202:203], v[178:179], v[208:209]
	v_rcp_f32_e32 v224, v221
	v_pk_fma_f32 v[200:201], v[190:191], v[200:201], v[202:203]
	s_nop 0
	v_pk_fma_f32 v[200:201], v[132:133], v[182:183], v[200:201]
	v_exp_f32_e32 v221, v223
	v_pk_add_f32 v[200:201], v[186:187], v[200:201]
	v_cvt_pk_bf16_f32 v218, v216, v217
	s_nop 0
	s_nop 0
	v_exp_f32_e32 v202, v200
	v_exp_f32_e32 v203, v201
	v_add_f32_e32 v221, 1.0, v221
	v_rcp_f32_e32 v225, v221
	v_add_f32_e32 v202, 1.0, v202
	v_add_f32_e32 v203, 1.0, v203
	v_pk_mul_f32 v[216:217], v[144:145], v[164:165]
	v_rcp_f32_e32 v202, v202
	v_rcp_f32_e32 v203, v203
	v_pk_fma_f32 v[216:217], v[196:197], v[212:213], v[216:217]
	v_pk_mul_f32 v[206:207], v[164:165], v[212:213]
	v_pk_fma_f32 v[216:217], v[136:137], v[170:171], v[216:217]
	v_pk_fma_f32 v[204:205], v[196:197], v[204:205], v[206:207]
	v_pk_add_f32 v[216:217], v[174:175], v[216:217]
	v_pk_mul_f32 v[222:223], v[222:223], v[224:225]
	v_pk_fma_f32 v[204:205], v[144:145], v[170:171], v[204:205]
	v_pk_mul_f32 v[216:217], v[216:217], v[222:223]
	v_pk_add_f32 v[204:205], v[174:175], v[204:205]
	v_pk_mul_f32 v[200:201], v[200:201], v[202:203]
	v_cvt_pk_bf16_f32 v221, v216, v217
	v_pk_mul_f32 v[200:201], v[204:205], v[200:201]
	v_cvt_pk_bf16_f32 v216, v198, v199
	v_add_co_u32_e32 v198, vcc, 0x2000, v248
	v_cvt_pk_bf16_f32 v217, v200, v201
	s_nop 0
	v_addc_co_u32_e32 v199, vcc, 0, v249, vcc
	global_store_dwordx4 v[248:249], v[214:217], off
	global_store_dwordx4 v[198:199], v[218:221], off offset:3072
.LBB0_706:
	s_andn2_saveexec_b64 s[2:3], s[4:5]
	s_or_b64 exec, exec, s[2:3]
	v_pk_mul_f32 v[212:213], v[8:9], v[192:193] op_sel:[0,1]
	v_mov_b32_e32 v8, v167
	v_pk_mul_f32 v[198:199], v[40:41], v[192:193] op_sel:[0,1]
	v_pk_mul_f32 v[210:211], v[30:31], v[192:193] op_sel:[0,1]
	v_pk_mul_f32 v[40:41], v[12:13], v[192:193] op_sel:[0,1]
	v_pk_mul_f32 v[12:13], v[6:7], v[192:193] op_sel:[0,1]
	v_pk_mul_f32 v[6:7], v[28:29], v[166:167] op_sel_hi:[1,0]
	v_pk_mul_f32 v[28:29], v[14:15], v[8:9] op_sel_hi:[1,0]
	v_pk_mul_f32 v[14:15], v[4:5], v[8:9] op_sel_hi:[1,0]
	v_pk_fma_f32 v[4:5], v[150:151], v[176:177], v[184:185]
	v_pk_mul_f32 v[202:203], v[52:53], v[192:193] op_sel_hi:[1,0]
	v_pk_fma_f32 v[4:5], v[210:211], v[188:189], v[4:5]
	v_pk_mul_f32 v[52:53], v[22:23], v[192:193] op_sel_hi:[1,0]
	v_pk_fma_f32 v[4:5], v[158:159], v[180:181], v[4:5]
	v_pk_mul_f32 v[204:205], v[18:19], v[192:193] op_sel_hi:[1,0]
	v_pk_mul_f32 v[30:31], v[36:37], v[166:167] op_sel_hi:[1,0]
	v_pk_mul_f32 v[22:23], v[34:35], v[166:167] op_sel_hi:[1,0]
	v_pk_mul_f32 v[36:37], v[26:27], v[166:167] op_sel_hi:[1,0]
	v_pk_mul_f32 v[18:19], v[48:49], v[8:9] op_sel_hi:[1,0]
	v_pk_mul_f32 v[34:35], v[46:47], v[8:9] op_sel_hi:[1,0]
	v_pk_mul_f32 v[44:45], v[44:45], v[8:9] op_sel_hi:[1,0]
	v_pk_mul_f32 v[42:43], v[42:43], v[8:9] op_sel_hi:[1,0]
	v_pk_mul_f32 v[26:27], v[16:17], v[8:9] op_sel_hi:[1,0]
	s_nop 0
	v_exp_f32_e32 v9, v4
	v_pk_fma_f32 v[16:17], v[146:147], v[162:163], v[172:173]
	v_pk_mul_f32 v[208:209], v[32:33], v[192:193] op_sel:[0,1]
	v_pk_fma_f32 v[16:17], v[12:13], v[194:195], v[16:17]
	v_pk_mul_f32 v[2:3], v[2:3], v[8:9] op_sel_hi:[1,0]
	s_nop 0
	v_exp_f32_e32 v46, v5
	v_add_f32_e32 v8, 1.0, v9
	v_rcp_f32_e32 v8, v8
	v_pk_fma_f32 v[16:17], v[154:155], v[168:169], v[16:17]
	v_add_f32_e32 v9, 1.0, v46
	v_rcp_f32_e32 v9, v9
	v_pk_mul_f32 v[206:207], v[50:51], v[192:193] op_sel_hi:[1,0]
	v_pk_fma_f32 v[46:47], v[148:149], v[164:165], v[174:175]
	v_pk_mul_f32 v[4:5], v[4:5], v[8:9]
	v_pk_fma_f32 v[8:9], v[152:153], v[178:179], v[186:187]
	v_pk_mul_f32 v[4:5], v[16:17], v[4:5]
	v_pk_fma_f32 v[8:9], v[208:209], v[190:191], v[8:9]
	v_cvt_pk_bf16_f32 v4, v4, v5
	v_pk_fma_f32 v[8:9], v[160:161], v[182:183], v[8:9]
	v_pk_fma_f32 v[46:47], v[212:213], v[196:197], v[46:47]
	v_pk_fma_f32 v[46:47], v[156:157], v[170:171], v[46:47]
	s_nop 0
	s_nop 0
	v_exp_f32_e32 v16, v8
	v_exp_f32_e32 v5, v9
	v_pk_mul_f32 v[20:21], v[20:21], v[192:193] op_sel_hi:[1,0]
	v_add_f32_e32 v16, 1.0, v16
	v_add_f32_e32 v5, 1.0, v5
	v_rcp_f32_e32 v16, v16
	v_rcp_f32_e32 v17, v5
	v_pk_fma_f32 v[48:49], v[212:213], v[164:165], v[174:175]
	v_pk_mul_f32 v[58:59], v[58:59], v[166:167] op_sel_hi:[1,0]
	v_pk_fma_f32 v[48:49], v[20:21], v[196:197], v[48:49]
	v_pk_mul_f32 v[8:9], v[8:9], v[16:17]
	v_pk_fma_f32 v[16:17], v[210:211], v[176:177], v[184:185]
	v_pk_mul_f32 v[8:9], v[46:47], v[8:9]
	v_pk_fma_f32 v[16:17], v[206:207], v[188:189], v[16:17]
	v_pk_fma_f32 v[48:49], v[148:149], v[170:171], v[48:49]
	v_pk_fma_f32 v[16:17], v[150:151], v[180:181], v[16:17]
	v_pk_mul_f32 v[50:51], v[24:25], v[192:193] op_sel_hi:[1,0]
	s_nop 0
	v_exp_f32_e32 v46, v16
	v_cvt_pk_bf16_f32 v5, v8, v9
	s_nop 0
	v_exp_f32_e32 v9, v17
	v_add_f32_e32 v8, 1.0, v46
	v_rcp_f32_e32 v8, v8
	v_pk_fma_f32 v[46:47], v[12:13], v[162:163], v[172:173]
	v_add_f32_e32 v9, 1.0, v9
; __device__ __forceinline__ unsigned cvt_pk_bf16(float lo, float hi) { f32x2c v = {lo, hi}; bf16x2c b = __builtin_convertvector(v, bf16x2c); return __builtin_bit_cast(unsigned, b); }
;     __device__ __forceinline__ void operator()(f32x4 (&acc)[2][2][4][2], const Unit& u, int wr, int wc, int fr_, int fq_) const {
;     ...
;             for (int j = 0; j < 8; ++j) { const f32x4 Gc = acc[j >> 2][0][j & 3][n], Vc = acc[j >> 2][1][j & 3][n];
;                 const f32x4 gc = wg0 * g2 + wg1 * g1 + wg2 * Gc + bg, vc = wv0 * v2 + wv1 * v1 + wv2 * Vc + bv; f32x4 o;
; #pragma unroll
;                 for (int i = 0; i < 4; ++i) o[i] = gc[i] * __builtin_amdgcn_rcpf(1.0f + __builtin_amdgcn_exp2f(gc[i] * -1.4426950408889634f)) * vc[i];
;                 pk[n][j].x = cvt_pk_bf16(o[0], o[1]); pk[n][j].y = cvt_pk_bf16(o[2], o[3]);
;                 g2 = g1; g1 = Gc; v2 = v1; v1 = Vc; } }
	v_rcp_f32_e32 v9, v9
	v_pk_fma_f32 v[46:47], v[204:205], v[194:195], v[46:47]
	v_pk_mul_f32 v[24:25], v[60:61], v[166:167] op_sel_hi:[1,0]
	v_pk_fma_f32 v[46:47], v[146:147], v[168:169], v[46:47]
	v_pk_mul_f32 v[8:9], v[16:17], v[8:9]
	v_pk_fma_f32 v[16:17], v[208:209], v[178:179], v[186:187]
	v_pk_fma_f32 v[16:17], v[202:203], v[190:191], v[16:17]
	v_pk_mul_f32 v[8:9], v[46:47], v[8:9]
	v_pk_fma_f32 v[16:17], v[152:153], v[182:183], v[16:17]
	v_cvt_pk_bf16_f32 v8, v8, v9
	v_pk_mul_f32 v[60:61], v[14:15], v[164:165]
	s_nop 0
	s_nop 0
	v_exp_f32_e32 v46, v16
	v_exp_f32_e32 v9, v17
	v_pk_fma_f32 v[60:61], v[6:7], v[196:197], v[60:61]
	v_pk_mul_f32 v[200:201], v[38:39], v[192:193] op_sel:[0,1]
	v_add_f32_e32 v46, 1.0, v46
	v_add_f32_e32 v9, 1.0, v9
	v_rcp_f32_e32 v46, v46
	v_rcp_f32_e32 v47, v9
	v_pk_mul_f32 v[10:11], v[10:11], v[192:193] op_sel:[0,1]
	v_pk_mul_f32 v[54:55], v[54:55], v[192:193] op_sel_hi:[1,0]
	v_pk_mul_f32 v[56:57], v[56:57], v[192:193] op_sel_hi:[1,0]
	v_pk_mul_f32 v[16:17], v[16:17], v[46:47]
	v_pk_fma_f32 v[46:47], v[206:207], v[176:177], v[184:185]
	v_pk_mul_f32 v[16:17], v[48:49], v[16:17]
	v_pk_fma_f32 v[46:47], v[42:43], v[188:189], v[46:47]
	v_pk_mul_f32 v[38:39], v[62:63], v[166:167] op_sel_hi:[1,0]
	v_pk_fma_f32 v[46:47], v[210:211], v[180:181], v[46:47]
	v_pk_mul_f32 v[32:33], v[64:65], v[166:167] op_sel_hi:[1,0]
	s_movk_i32 s2, 0x5000
	s_nop 0
	v_exp_f32_e32 v48, v46
	v_cvt_pk_bf16_f32 v9, v16, v17
	s_nop 0
	v_exp_f32_e32 v17, v47
	v_add_f32_e32 v16, 1.0, v48
	v_rcp_f32_e32 v16, v16
	v_pk_mul_f32 v[48:49], v[204:205], v[162:163]
	v_add_f32_e32 v17, 1.0, v17
	v_rcp_f32_e32 v17, v17
	v_pk_fma_f32 v[48:49], v[2:3], v[194:195], v[48:49]
	v_pk_mul_f32 v[16:17], v[46:47], v[16:17]
	v_pk_fma_f32 v[12:13], v[12:13], v[168:169], v[48:49]
	v_pk_fma_f32 v[48:49], v[20:21], v[164:165], v[174:175]
	v_pk_add_f32 v[12:13], v[172:173], v[12:13]
	v_pk_fma_f32 v[48:49], v[14:15], v[196:197], v[48:49]
	v_pk_mul_f32 v[12:13], v[12:13], v[16:17]
	v_pk_fma_f32 v[16:17], v[202:203], v[178:179], v[186:187]
	v_cvt_pk_bf16_f32 v12, v12, v13
	v_pk_fma_f32 v[16:17], v[44:45], v[190:191], v[16:17]
	v_pk_fma_f32 v[48:49], v[212:213], v[170:171], v[48:49]
	v_pk_fma_f32 v[16:17], v[208:209], v[182:183], v[16:17]
	v_pk_fma_f32 v[20:21], v[20:21], v[170:171], v[60:61]
	s_nop 0
	s_nop 0
	v_exp_f32_e32 v46, v16
	v_exp_f32_e32 v13, v17
	v_pk_add_f32 v[20:21], v[174:175], v[20:21]
	v_add_f32_e32 v46, 1.0, v46
	v_add_f32_e32 v13, 1.0, v13
	v_rcp_f32_e32 v46, v46
	v_rcp_f32_e32 v47, v13
	s_nop 0
	v_pk_mul_f32 v[16:17], v[16:17], v[46:47]
	v_pk_fma_f32 v[46:47], v[42:43], v[176:177], v[184:185]
	v_pk_mul_f32 v[16:17], v[48:49], v[16:17]
	v_pk_fma_f32 v[46:47], v[58:59], v[188:189], v[46:47]
	s_nop 0
	v_pk_fma_f32 v[46:47], v[206:207], v[180:181], v[46:47]
	s_nop 0
	s_nop 0
	s_nop 0
	v_exp_f32_e32 v48, v46
	v_cvt_pk_bf16_f32 v13, v16, v17
	s_nop 0
	v_exp_f32_e32 v17, v47
	v_add_f32_e32 v16, 1.0, v48
	v_rcp_f32_e32 v16, v16
	v_pk_fma_f32 v[48:49], v[2:3], v[162:163], v[172:173]
	v_add_f32_e32 v17, 1.0, v17
	v_rcp_f32_e32 v17, v17
	v_pk_fma_f32 v[48:49], v[36:37], v[194:195], v[48:49]
	v_pk_mul_f32 v[16:17], v[46:47], v[16:17]
	v_pk_fma_f32 v[46:47], v[44:45], v[178:179], v[186:187]
	v_pk_fma_f32 v[48:49], v[204:205], v[168:169], v[48:49]
	v_pk_fma_f32 v[46:47], v[24:25], v[190:191], v[46:47]
	v_pk_fma_f32 v[46:47], v[202:203], v[182:183], v[46:47]
	v_pk_mul_f32 v[16:17], v[48:49], v[16:17]
	v_cvt_pk_bf16_f32 v16, v16, v17
	s_nop 0
	s_nop 0
	v_exp_f32_e32 v48, v46
	v_exp_f32_e32 v17, v47
	v_add_f32_e32 v48, 1.0, v48
	v_add_f32_e32 v17, 1.0, v17
	v_rcp_f32_e32 v48, v48
	v_rcp_f32_e32 v49, v17
	s_nop 0
	v_pk_mul_f32 v[46:47], v[46:47], v[48:49]
	s_nop 0
	v_pk_mul_f32 v[20:21], v[20:21], v[46:47]
	v_pk_mul_f32 v[46:47], v[58:59], v[176:177]
	s_nop 0
	v_pk_fma_f32 v[46:47], v[138:139], v[188:189], v[46:47]
	s_nop 0
	v_pk_fma_f32 v[42:43], v[42:43], v[180:181], v[46:47]
	s_nop 0
	v_pk_add_f32 v[42:43], v[184:185], v[42:43]
	s_nop 0
	s_nop 0
	v_exp_f32_e32 v46, v42
	v_cvt_pk_bf16_f32 v17, v20, v21
	s_nop 0
	v_exp_f32_e32 v21, v43
	v_add_f32_e32 v20, 1.0, v46
	v_rcp_f32_e32 v20, v20
	v_pk_mul_f32 v[46:47], v[36:37], v[162:163]
	v_add_f32_e32 v21, 1.0, v21
	v_rcp_f32_e32 v21, v21
	v_pk_fma_f32 v[46:47], v[134:135], v[194:195], v[46:47]
	v_pk_mul_f32 v[20:21], v[42:43], v[20:21]
	v_pk_fma_f32 v[2:3], v[2:3], v[168:169], v[46:47]
	s_nop 0
	v_pk_add_f32 v[2:3], v[172:173], v[2:3]
	s_nop 0
	v_pk_mul_f32 v[2:3], v[2:3], v[20:21]
	v_pk_mul_f32 v[20:21], v[24:25], v[178:179]
	s_nop 0
	v_pk_fma_f32 v[20:21], v[140:141], v[190:191], v[20:21]
	s_nop 0
	v_pk_fma_f32 v[20:21], v[44:45], v[182:183], v[20:21]
	v_pk_mul_f32 v[44:45], v[6:7], v[164:165]
	v_pk_add_f32 v[42:43], v[186:187], v[20:21]
	v_pk_fma_f32 v[44:45], v[136:137], v[196:197], v[44:45]
	s_nop 0
	v_exp_f32_e32 v21, v42
	v_cvt_pk_bf16_f32 v20, v2, v3
	s_nop 0
	v_exp_f32_e32 v3, v43
	v_add_f32_e32 v2, 1.0, v21
	v_rcp_f32_e32 v2, v2
	v_pk_fma_f32 v[14:15], v[14:15], v[170:171], v[44:45]
	v_add_f32_e32 v3, 1.0, v3
	v_rcp_f32_e32 v3, v3
	v_pk_add_f32 v[14:15], v[174:175], v[14:15]
	v_pk_mul_f32 v[2:3], v[42:43], v[2:3]
	v_pk_fma_f32 v[42:43], v[130:131], v[188:189], v[184:185]
	v_pk_mul_f32 v[2:3], v[14:15], v[2:3]
	v_pk_fma_f32 v[42:43], v[138:139], v[176:177], v[42:43]
	v_pk_fma_f32 v[14:15], v[142:143], v[194:195], v[172:173]
	v_pk_fma_f32 v[42:43], v[58:59], v[180:181], v[42:43]
	v_pk_fma_f32 v[14:15], v[134:135], v[162:163], v[14:15]
	v_pk_fma_f32 v[14:15], v[36:37], v[168:169], v[14:15]
	s_nop 0
	v_exp_f32_e32 v46, v42
	s_nop 0
	v_exp_f32_e32 v47, v43
	v_pk_mul_f32 v[44:45], v[132:133], v[190:191]
; __device__ __forceinline__ unsigned cvt_pk_bf16(float lo, float hi) { f32x2c v = {lo, hi}; bf16x2c b = __builtin_convertvector(v, bf16x2c); return __builtin_bit_cast(unsigned, b); }
;     __device__ __forceinline__ void operator()(f32x4 (&acc)[2][2][4][2], const Unit& u, int wr, int wc, int fr_, int fq_) const {
;     ...
;             for (int j = 0; j < 8; ++j) { const f32x4 Gc = acc[j >> 2][0][j & 3][n], Vc = acc[j >> 2][1][j & 3][n];
;                 const f32x4 gc = wg0 * g2 + wg1 * g1 + wg2 * Gc + bg, vc = wv0 * v2 + wv1 * v1 + wv2 * Vc + bv; f32x4 o;
; #pragma unroll
;                 for (int i = 0; i < 4; ++i) o[i] = gc[i] * __builtin_amdgcn_rcpf(1.0f + __builtin_amdgcn_exp2f(gc[i] * -1.4426950408889634f)) * vc[i];
;                 pk[n][j].x = cvt_pk_bf16(o[0], o[1]); pk[n][j].y = cvt_pk_bf16(o[2], o[3]);
;                 g2 = g1; g1 = Gc; v2 = v1; v1 = Vc; } }
	v_add_f32_e32 v46, 1.0, v46
	v_rcp_f32_e32 v46, v46
	v_add_f32_e32 v47, 1.0, v47
	v_rcp_f32_e32 v47, v47
	v_cvt_pk_bf16_f32 v21, v2, v3
	v_pk_fma_f32 v[2:3], v[144:145], v[196:197], v[174:175]
	v_pk_mul_f32 v[36:37], v[42:43], v[46:47]
	v_pk_fma_f32 v[2:3], v[136:137], v[164:165], v[2:3]
	v_pk_mul_f32 v[14:15], v[14:15], v[36:37]
	v_pk_fma_f32 v[36:37], v[140:141], v[178:179], v[44:45]
	v_pk_fma_f32 v[2:3], v[6:7], v[170:171], v[2:3]
	v_pk_fma_f32 v[24:25], v[24:25], v[182:183], v[36:37]
	v_pk_add_f32 v[36:37], v[186:187], v[24:25]
	s_nop 0
	s_nop 0
	v_exp_f32_e32 v25, v36
	s_nop 0
	v_exp_f32_e32 v42, v37
	v_cvt_pk_bf16_f32 v24, v14, v15
	v_add_f32_e32 v14, 1.0, v25
	v_rcp_f32_e32 v14, v14
	v_add_f32_e32 v15, 1.0, v42
	v_rcp_f32_e32 v15, v15
	v_pk_fma_f32 v[42:43], v[40:41], v[104:105], v[100:101]
	v_pk_mul_f32 v[6:7], v[36:37], v[14:15]
	s_nop 0
	v_pk_mul_f32 v[2:3], v[2:3], v[6:7]
	v_pk_fma_f32 v[6:7], v[86:87], v[110:111], v[118:119]
	v_cvt_pk_bf16_f32 v25, v2, v3
	v_pk_fma_f32 v[6:7], v[200:201], v[106:107], v[6:7]
	v_pk_fma_f32 v[36:37], v[84:85], v[104:105], v[100:101]
	v_pk_fma_f32 v[6:7], v[126:127], v[114:115], v[6:7]
	v_pk_fma_f32 v[36:37], v[40:41], v[92:93], v[36:37]
	v_pk_fma_f32 v[36:37], v[124:125], v[96:97], v[36:37]
	s_nop 0
	s_nop 0
	v_exp_f32_e32 v14, v6
	v_exp_f32_e32 v3, v7
	v_pk_fma_f32 v[42:43], v[50:51], v[92:93], v[42:43]
	v_add_f32_e32 v2, 1.0, v14
	v_add_f32_e32 v3, 1.0, v3
	v_rcp_f32_e32 v2, v2
	v_rcp_f32_e32 v3, v3
	v_pk_fma_f32 v[14:15], v[82:83], v[102:103], v[98:99]
	v_pk_fma_f32 v[42:43], v[84:85], v[96:97], v[42:43]
	v_pk_fma_f32 v[14:15], v[10:11], v[90:91], v[14:15]
	v_pk_mul_f32 v[2:3], v[6:7], v[2:3]
	v_pk_fma_f32 v[6:7], v[88:89], v[112:113], v[120:121]
	v_pk_fma_f32 v[14:15], v[122:123], v[94:95], v[14:15]
	v_pk_fma_f32 v[6:7], v[198:199], v[108:109], v[6:7]
	v_pk_fma_f32 v[6:7], v[128:129], v[116:117], v[6:7]
	v_pk_mul_f32 v[2:3], v[14:15], v[2:3]
	v_cvt_pk_bf16_f32 v2, v2, v3
	s_nop 0
	s_nop 0
	v_exp_f32_e32 v14, v6
	v_exp_f32_e32 v3, v7
	v_add_f32_e32 v14, 1.0, v14
	v_add_f32_e32 v3, 1.0, v3
	v_rcp_f32_e32 v14, v14
	v_rcp_f32_e32 v15, v3
	s_nop 0
	v_pk_mul_f32 v[6:7], v[6:7], v[14:15]
	v_pk_fma_f32 v[14:15], v[200:201], v[110:111], v[118:119]
	v_pk_mul_f32 v[6:7], v[36:37], v[6:7]
	v_pk_fma_f32 v[14:15], v[54:55], v[106:107], v[14:15]
	s_nop 0
	v_pk_fma_f32 v[14:15], v[86:87], v[114:115], v[14:15]
	s_nop 0
	s_nop 0
	s_nop 0
	v_exp_f32_e32 v36, v14
	v_cvt_pk_bf16_f32 v3, v6, v7
	s_nop 0
	v_exp_f32_e32 v7, v15
	v_add_f32_e32 v6, 1.0, v36
	v_rcp_f32_e32 v6, v6
	v_pk_fma_f32 v[36:37], v[10:11], v[102:103], v[98:99]
	v_add_f32_e32 v7, 1.0, v7
	v_rcp_f32_e32 v7, v7
	v_pk_fma_f32 v[36:37], v[52:53], v[90:91], v[36:37]
	v_pk_mul_f32 v[6:7], v[14:15], v[6:7]
	v_pk_fma_f32 v[14:15], v[198:199], v[112:113], v[120:121]
	v_pk_fma_f32 v[36:37], v[82:83], v[94:95], v[36:37]
	v_pk_fma_f32 v[14:15], v[56:57], v[108:109], v[14:15]
	v_pk_fma_f32 v[14:15], v[88:89], v[116:117], v[14:15]
	v_pk_mul_f32 v[6:7], v[36:37], v[6:7]
	v_cvt_pk_bf16_f32 v6, v6, v7
	s_nop 0
	s_nop 0
	v_exp_f32_e32 v36, v14
	v_exp_f32_e32 v7, v15
	v_add_f32_e32 v36, 1.0, v36
	v_add_f32_e32 v7, 1.0, v7
	v_rcp_f32_e32 v36, v36
	v_rcp_f32_e32 v37, v7
	s_nop 0
	v_pk_mul_f32 v[14:15], v[14:15], v[36:37]
	v_pk_fma_f32 v[36:37], v[54:55], v[110:111], v[118:119]
	v_pk_mul_f32 v[14:15], v[42:43], v[14:15]
	v_pk_fma_f32 v[36:37], v[34:35], v[106:107], v[36:37]
	s_nop 0
	v_pk_fma_f32 v[36:37], v[200:201], v[114:115], v[36:37]
	s_nop 0
	s_nop 0
	s_nop 0
	v_exp_f32_e32 v42, v36
	v_cvt_pk_bf16_f32 v7, v14, v15
	s_nop 0
	v_exp_f32_e32 v15, v37
	v_add_f32_e32 v14, 1.0, v42
	v_rcp_f32_e32 v14, v14
	v_pk_mul_f32 v[42:43], v[52:53], v[102:103]
	v_add_f32_e32 v15, 1.0, v15
	v_rcp_f32_e32 v15, v15
	v_pk_fma_f32 v[42:43], v[28:29], v[90:91], v[42:43]
	v_pk_mul_f32 v[14:15], v[36:37], v[14:15]
	v_pk_fma_f32 v[10:11], v[10:11], v[94:95], v[42:43]
	v_pk_mul_f32 v[42:43], v[50:51], v[104:105]
	v_pk_add_f32 v[10:11], v[98:99], v[10:11]
	v_pk_fma_f32 v[42:43], v[26:27], v[92:93], v[42:43]
	v_pk_mul_f32 v[10:11], v[10:11], v[14:15]
	v_pk_fma_f32 v[14:15], v[56:57], v[112:113], v[120:121]
	v_cvt_pk_bf16_f32 v10, v10, v11
	v_pk_fma_f32 v[14:15], v[18:19], v[108:109], v[14:15]
	v_pk_fma_f32 v[40:41], v[40:41], v[96:97], v[42:43]
	v_pk_fma_f32 v[14:15], v[198:199], v[116:117], v[14:15]
	v_pk_add_f32 v[40:41], v[100:101], v[40:41]
	v_pk_fma_f32 v[42:43], v[26:27], v[104:105], v[100:101]
	s_nop 0
	s_nop 0
	v_exp_f32_e32 v36, v14
	v_exp_f32_e32 v11, v15
	v_pk_fma_f32 v[42:43], v[30:31], v[92:93], v[42:43]
	v_add_f32_e32 v36, 1.0, v36
	v_add_f32_e32 v11, 1.0, v11
	v_rcp_f32_e32 v36, v36
	v_rcp_f32_e32 v37, v11
	v_pk_fma_f32 v[42:43], v[50:51], v[96:97], v[42:43]
	v_pk_mul_f32 v[14:15], v[14:15], v[36:37]
	v_pk_fma_f32 v[36:37], v[34:35], v[110:111], v[118:119]
	v_pk_mul_f32 v[14:15], v[40:41], v[14:15]
	v_pk_fma_f32 v[36:37], v[38:39], v[106:107], v[36:37]
	v_pk_fma_f32 v[36:37], v[54:55], v[114:115], v[36:37]
; __device__ __forceinline__ unsigned cvt_pk_bf16(float lo, float hi) { f32x2c v = {lo, hi}; bf16x2c b = __builtin_convertvector(v, bf16x2c); return __builtin_bit_cast(unsigned, b); }
;     __device__ __forceinline__ void operator()(f32x4 (&acc)[2][2][4][2], const Unit& u, int wr, int wc, int fr_, int fq_) const {
;     ...
;             for (int j = 0; j < 8; ++j) { const f32x4 Gc = acc[j >> 2][0][j & 3][n], Vc = acc[j >> 2][1][j & 3][n];
;                 const f32x4 gc = wg0 * g2 + wg1 * g1 + wg2 * Gc + bg, vc = wv0 * v2 + wv1 * v1 + wv2 * Vc + bv; f32x4 o;
; #pragma unroll
;                 for (int i = 0; i < 4; ++i) o[i] = gc[i] * __builtin_amdgcn_rcpf(1.0f + __builtin_amdgcn_exp2f(gc[i] * -1.4426950408889634f)) * vc[i];
;                 pk[n][j].x = cvt_pk_bf16(o[0], o[1]); pk[n][j].y = cvt_pk_bf16(o[2], o[3]);
;                 g2 = g1; g1 = Gc; v2 = v1; v1 = Vc; } }
;         bf16_t* ap = act + (size_t)(u.pm * BM + t0) * DFF_ + u.pn * HALF + colb;
; #pragma unroll
;         for (int j = 0; j < 8; ++j) if (!(defer01 && j < 2)) *(u32x4*)(ap + (size_t)j * DFF_) = (u32x4){pk[0][j].x, pk[0][j].y, pk[1][j].x, pk[1][j].y};
	s_nop 0
	s_nop 0
	s_nop 0
	v_exp_f32_e32 v40, v36
	v_cvt_pk_bf16_f32 v11, v14, v15
	s_nop 0
	v_exp_f32_e32 v15, v37
	v_add_f32_e32 v14, 1.0, v40
	v_rcp_f32_e32 v14, v14
	v_pk_fma_f32 v[40:41], v[28:29], v[102:103], v[98:99]
	v_add_f32_e32 v15, 1.0, v15
	v_rcp_f32_e32 v15, v15
	v_pk_fma_f32 v[40:41], v[22:23], v[90:91], v[40:41]
	v_pk_mul_f32 v[14:15], v[36:37], v[14:15]
	v_pk_fma_f32 v[36:37], v[18:19], v[112:113], v[120:121]
	v_pk_fma_f32 v[40:41], v[52:53], v[94:95], v[40:41]
	v_pk_fma_f32 v[36:37], v[32:33], v[108:109], v[36:37]
	v_pk_fma_f32 v[36:37], v[56:57], v[116:117], v[36:37]
	v_pk_mul_f32 v[14:15], v[40:41], v[14:15]
	v_cvt_pk_bf16_f32 v14, v14, v15
	s_nop 0
	s_nop 0
	v_exp_f32_e32 v40, v36
	v_exp_f32_e32 v15, v37
	v_add_f32_e32 v40, 1.0, v40
	v_add_f32_e32 v15, 1.0, v15
	v_rcp_f32_e32 v40, v40
	v_rcp_f32_e32 v41, v15
	s_nop 0
	v_pk_mul_f32 v[36:37], v[36:37], v[40:41]
	v_pk_mul_f32 v[40:41], v[38:39], v[110:111]
	v_pk_mul_f32 v[36:37], v[42:43], v[36:37]
	v_pk_fma_f32 v[40:41], v[74:75], v[106:107], v[40:41]
	s_nop 0
	v_pk_fma_f32 v[34:35], v[34:35], v[114:115], v[40:41]
	s_nop 0
	v_pk_add_f32 v[34:35], v[118:119], v[34:35]
	s_nop 0
	s_nop 0
	v_exp_f32_e32 v40, v34
	v_cvt_pk_bf16_f32 v15, v36, v37
	s_nop 0
	v_exp_f32_e32 v37, v35
	v_add_f32_e32 v36, 1.0, v40
	v_rcp_f32_e32 v36, v36
	v_pk_mul_f32 v[40:41], v[22:23], v[102:103]
	v_add_f32_e32 v37, 1.0, v37
	v_rcp_f32_e32 v37, v37
	v_pk_fma_f32 v[40:41], v[78:79], v[90:91], v[40:41]
	v_pk_mul_f32 v[34:35], v[34:35], v[36:37]
	v_pk_fma_f32 v[28:29], v[28:29], v[94:95], v[40:41]
	v_pk_mul_f32 v[36:37], v[30:31], v[104:105]
	v_pk_add_f32 v[28:29], v[98:99], v[28:29]
	v_pk_fma_f32 v[36:37], v[80:81], v[92:93], v[36:37]
	v_pk_mul_f32 v[28:29], v[28:29], v[34:35]
	v_pk_mul_f32 v[34:35], v[32:33], v[112:113]
	v_pk_fma_f32 v[26:27], v[26:27], v[96:97], v[36:37]
	v_pk_fma_f32 v[34:35], v[76:77], v[108:109], v[34:35]
	v_pk_add_f32 v[26:27], v[100:101], v[26:27]
	v_pk_fma_f32 v[18:19], v[18:19], v[116:117], v[34:35]
	s_nop 0
	v_pk_add_f32 v[34:35], v[120:121], v[18:19]
	s_nop 0
	s_nop 0
	v_exp_f32_e32 v19, v34
	v_cvt_pk_bf16_f32 v18, v28, v29
	s_nop 0
	v_exp_f32_e32 v29, v35
	v_add_f32_e32 v19, 1.0, v19
	v_rcp_f32_e32 v28, v19
	v_add_f32_e32 v19, 1.0, v29
	v_rcp_f32_e32 v29, v19
	s_nop 0
	v_pk_mul_f32 v[28:29], v[34:35], v[28:29]
	s_nop 0
	v_pk_mul_f32 v[26:27], v[26:27], v[28:29]
	s_nop 0
	v_cvt_pk_bf16_f32 v19, v26, v27
	v_pk_fma_f32 v[26:27], v[74:75], v[110:111], v[118:119]
	s_nop 0
	v_pk_fma_f32 v[26:27], v[70:71], v[106:107], v[26:27]
	s_nop 0
	v_pk_fma_f32 v[26:27], v[38:39], v[114:115], v[26:27]
	s_nop 0
	s_nop 0
	s_nop 0
	v_exp_f32_e32 v34, v26
	s_nop 0
	v_exp_f32_e32 v35, v27
	v_pk_mul_f32 v[28:29], v[78:79], v[102:103]
	v_add_f32_e32 v34, 1.0, v34
	v_rcp_f32_e32 v34, v34
	v_add_f32_e32 v35, 1.0, v35
	v_rcp_f32_e32 v35, v35
	v_pk_fma_f32 v[28:29], v[66:67], v[90:91], v[28:29]
	v_pk_mul_f32 v[26:27], v[26:27], v[34:35]
	v_pk_fma_f32 v[22:23], v[22:23], v[94:95], v[28:29]
	s_nop 0
	v_pk_add_f32 v[22:23], v[98:99], v[22:23]
	s_nop 0
	v_pk_mul_f32 v[22:23], v[22:23], v[26:27]
	v_pk_fma_f32 v[26:27], v[76:77], v[112:113], v[120:121]
	v_cvt_pk_bf16_f32 v22, v22, v23
	v_pk_fma_f32 v[26:27], v[72:73], v[108:109], v[26:27]
	s_nop 0
	v_pk_fma_f32 v[26:27], v[32:33], v[116:117], v[26:27]
	s_nop 0
	s_nop 0
	s_nop 0
	v_exp_f32_e32 v23, v26
	s_nop 0
	v_exp_f32_e32 v33, v27
	v_pk_fma_f32 v[28:29], v[80:81], v[104:105], v[100:101]
	v_add_f32_e32 v23, 1.0, v23
	v_rcp_f32_e32 v32, v23
	v_add_f32_e32 v23, 1.0, v33
	v_rcp_f32_e32 v33, v23
	v_pk_fma_f32 v[28:29], v[68:69], v[92:93], v[28:29]
	v_pk_mul_f32 v[26:27], v[26:27], v[32:33]
	v_pk_fma_f32 v[28:29], v[30:31], v[96:97], v[28:29]
	s_nop 0
	s_nop 0
	v_pk_mul_f32 v[26:27], v[28:29], v[26:27]
	s_nop 0
	v_cvt_pk_bf16_f32 v23, v26, v27
	v_add_co_u32_e32 v26, vcc, s2, v248
	s_mov_b32 s2, 0xb000
	s_nop 0
	v_addc_co_u32_e32 v27, vcc, 0, v249, vcc
	global_store_dwordx4 v[26:27], v[22:25], off offset:2048
	s_nop 1
	v_add_co_u32_e32 v22, vcc, s18, v248
	s_nop 1
	v_addc_co_u32_e32 v23, vcc, 0, v249, vcc
	global_store_dwordx4 v[22:23], v[18:21], off offset:1024
	s_nop 1
	v_add_co_u32_e32 v18, vcc, s2, v248
	s_mov_b32 s2, 0xd000
	s_nop 0
	v_addc_co_u32_e32 v19, vcc, 0, v249, vcc
	global_store_dwordx4 v[18:19], v[14:17], off
	s_nop 1
	v_add_co_u32_e32 v14, vcc, s2, v248
	s_mov_b64 s[2:3], -1
	s_nop 0
	v_addc_co_u32_e32 v15, vcc, 0, v249, vcc
	global_store_dwordx4 v[14:15], v[10:13], off offset:3072
	s_nop 1
	v_add_co_u32_e32 v10, vcc, 0x10000, v248
	s_nop 1
	v_addc_co_u32_e32 v11, vcc, 0, v249, vcc
	global_store_dwordx4 v[10:11], v[6:9], off offset:2048
	s_nop 1
	v_add_co_u32_e32 v6, vcc, 0x13000, v248
	s_nop 1
	v_addc_co_u32_e32 v7, vcc, 0, v249, vcc
	s_and_b64 vcc, exec, s[8:9]
	global_store_dwordx4 v[6:7], v[2:5], off offset:1024
	s_cbranch_vccnz .LBB0_685
	s_andn2_b64 vcc, exec, s[14:15]
	s_cbranch_vccnz .LBB0_684
	s_barrier
	s_branch .LBB0_684
